# ssm3 carried-state (F-table) part regenerated with 24 loads in flight
# speedup vs baseline: 1.0084x; 1.0084x over previous
.LBB0_434:
	s_lshl_b64 s[0:1], s[34:35], 18
	v_readlane_b32 s2, v253, 14
	s_add_u32 s0, s2, s0
	v_readlane_b32 s2, v253, 7
	s_addc_u32 s1, s2, s1
	v_lshlrev_b32_e32 v0, 8, v93
	v_lshl_add_u64 v[2:3], s[0:1], 0, v[0:1]
	v_mov_b32_e32 v91, v1
	v_ashrrev_i32_e32 v89, 31, v88
	v_lshl_add_u64 v[72:73], v[2:3], 0, v[90:91]
	v_lshlrev_b64 v[2:3], 12, v[88:89]
	v_lshl_add_u64 v[74:75], v[72:73], 0, v[2:3]
	s_mov_b64 s[0:1], 0x4000
	global_load_dwordx4 v[102:105], v[74:75], off offset:0
	global_load_dwordx4 v[106:109], v[74:75], off offset:64
	global_load_dwordx4 v[110:113], v[74:75], off offset:128
	global_load_dwordx4 v[114:117], v[74:75], off offset:192
	v_lshl_add_u64 v[74:75], v[74:75], 0, s[0:1]
	global_load_dwordx4 v[118:121], v[74:75], off offset:0
	global_load_dwordx4 v[122:125], v[74:75], off offset:64
	global_load_dwordx4 v[126:129], v[74:75], off offset:128
	global_load_dwordx4 v[130:133], v[74:75], off offset:192
	v_lshl_add_u64 v[74:75], v[74:75], 0, s[0:1]
	global_load_dwordx4 v[134:137], v[74:75], off offset:0
	global_load_dwordx4 v[138:141], v[74:75], off offset:64
	global_load_dwordx4 v[142:145], v[74:75], off offset:128
	global_load_dwordx4 v[146:149], v[74:75], off offset:192
	v_lshl_add_u64 v[74:75], v[74:75], 0, s[0:1]
	global_load_dwordx4 v[150:153], v[74:75], off offset:0
	global_load_dwordx4 v[154:157], v[74:75], off offset:64
	global_load_dwordx4 v[158:161], v[74:75], off offset:128
	global_load_dwordx4 v[162:165], v[74:75], off offset:192
	v_lshl_add_u64 v[74:75], v[74:75], 0, s[0:1]
	global_load_dwordx4 v[214:217], v[74:75], off offset:0
	global_load_dwordx4 v[218:221], v[74:75], off offset:64
	global_load_dwordx4 v[222:225], v[74:75], off offset:128
	global_load_dwordx4 v[226:229], v[74:75], off offset:192
	v_lshl_add_u64 v[74:75], v[74:75], 0, s[0:1]
	global_load_dwordx4 v[230:233], v[74:75], off offset:0
	global_load_dwordx4 v[234:237], v[74:75], off offset:64
	global_load_dwordx4 v[238:241], v[74:75], off offset:128
	global_load_dwordx4 v[242:245], v[74:75], off offset:192
	v_lshl_add_u64 v[74:75], v[74:75], 0, s[0:1]
	v_mul_u32_u24_e32 v0, 0xe0, v93
	v_add3_u32 v0, v95, v0, v90
	ds_read_b128 v[68:71], v0
	ds_read_b128 v[76:79], v0 offset:64
	ds_read_b128 v[80:83], v0 offset:128
	ds_read_b128 v[84:87], v0 offset:192
	v_readlane_b32 s2, v253, 36
	v_readlane_b32 s3, v253, 37
	s_lshl_b32 s98, s23, 4
	s_add_i32 s98, s98, s22
	s_mul_hi_i32 s99, s98, 0x120000
	s_mul_i32 s98, s98, 0x120000
	s_add_u32 s2, s2, s98
	s_addc_u32 s3, s3, s99
	v_add_u32_e32 v2, v100, v88
	v_ashrrev_i32_e32 v3, 31, v2
	v_lshlrev_b64 v[2:3], 6, v[2:3]
	v_lshl_add_u64 v[88:89], s[2:3], 0, v[90:91]
	v_lshl_add_u64 v[88:89], v[88:89], 0, v[2:3]
	s_waitcnt lgkmcnt(0)
	s_waitcnt vmcnt(20)
	v_mfma_f32_16x16x32_bf16 v[16:19], v[102:105], v[68:71], v[16:19]
	v_mfma_f32_16x16x32_bf16 v[16:19], v[106:109], v[76:79], v[16:19]
	v_mfma_f32_16x16x32_bf16 v[16:19], v[110:113], v[80:83], v[16:19]
	v_mfma_f32_16x16x32_bf16 v[16:19], v[114:117], v[84:87], v[16:19]
	global_load_dwordx4 v[102:105], v[74:75], off offset:0
	global_load_dwordx4 v[106:109], v[74:75], off offset:64
	global_load_dwordx4 v[110:113], v[74:75], off offset:128
	global_load_dwordx4 v[114:117], v[74:75], off offset:192
	v_lshl_add_u64 v[74:75], v[74:75], 0, s[0:1]
	s_waitcnt vmcnt(20)
	v_mfma_f32_16x16x32_bf16 v[12:15], v[118:121], v[68:71], v[12:15]
	v_mfma_f32_16x16x32_bf16 v[12:15], v[122:125], v[76:79], v[12:15]
	v_mfma_f32_16x16x32_bf16 v[12:15], v[126:129], v[80:83], v[12:15]
	v_mfma_f32_16x16x32_bf16 v[12:15], v[130:133], v[84:87], v[12:15]
	global_load_dwordx4 v[118:121], v[74:75], off offset:0
	global_load_dwordx4 v[122:125], v[74:75], off offset:64
	global_load_dwordx4 v[126:129], v[74:75], off offset:128
	global_load_dwordx4 v[130:133], v[74:75], off offset:192
	v_lshl_add_u64 v[74:75], v[74:75], 0, s[0:1]
	s_waitcnt vmcnt(20)
	v_mfma_f32_16x16x32_bf16 v[8:11], v[134:137], v[68:71], v[8:11]
	v_mfma_f32_16x16x32_bf16 v[8:11], v[138:141], v[76:79], v[8:11]
	v_mfma_f32_16x16x32_bf16 v[8:11], v[142:145], v[80:83], v[8:11]
	v_mfma_f32_16x16x32_bf16 v[8:11], v[146:149], v[84:87], v[8:11]
	global_load_dwordx4 v[134:137], v[74:75], off offset:0
	global_load_dwordx4 v[138:141], v[74:75], off offset:64
	global_load_dwordx4 v[142:145], v[74:75], off offset:128
	global_load_dwordx4 v[146:149], v[74:75], off offset:192
	v_lshl_add_u64 v[74:75], v[74:75], 0, s[0:1]
	s_waitcnt vmcnt(20)
	v_mfma_f32_16x16x32_bf16 v[4:7], v[150:153], v[68:71], v[4:7]
	v_mfma_f32_16x16x32_bf16 v[4:7], v[154:157], v[76:79], v[4:7]
	v_mfma_f32_16x16x32_bf16 v[4:7], v[158:161], v[80:83], v[4:7]
	v_mfma_f32_16x16x32_bf16 v[4:7], v[162:165], v[84:87], v[4:7]
	global_load_dwordx4 v[150:153], v[74:75], off offset:0
	global_load_dwordx4 v[154:157], v[74:75], off offset:64
	global_load_dwordx4 v[158:161], v[74:75], off offset:128
	global_load_dwordx4 v[162:165], v[74:75], off offset:192
	v_lshl_add_u64 v[74:75], v[74:75], 0, s[0:1]
	s_waitcnt vmcnt(20)
	v_mfma_f32_16x16x32_bf16 v[32:35], v[214:217], v[68:71], v[32:35]
	v_mfma_f32_16x16x32_bf16 v[32:35], v[218:221], v[76:79], v[32:35]
	v_mfma_f32_16x16x32_bf16 v[32:35], v[222:225], v[80:83], v[32:35]
	v_mfma_f32_16x16x32_bf16 v[32:35], v[226:229], v[84:87], v[32:35]
	global_load_dwordx4 v[214:217], v[74:75], off offset:0
	global_load_dwordx4 v[218:221], v[74:75], off offset:64
	global_load_dwordx4 v[222:225], v[74:75], off offset:128
	global_load_dwordx4 v[226:229], v[74:75], off offset:192
	v_lshl_add_u64 v[74:75], v[74:75], 0, s[0:1]
	s_waitcnt vmcnt(20)
	v_mfma_f32_16x16x32_bf16 v[28:31], v[230:233], v[68:71], v[28:31]
	v_mfma_f32_16x16x32_bf16 v[28:31], v[234:237], v[76:79], v[28:31]
	v_mfma_f32_16x16x32_bf16 v[28:31], v[238:241], v[80:83], v[28:31]
	v_mfma_f32_16x16x32_bf16 v[28:31], v[242:245], v[84:87], v[28:31]
	global_load_dwordx4 v[230:233], v[74:75], off offset:0
	global_load_dwordx4 v[234:237], v[74:75], off offset:64
	global_load_dwordx4 v[238:241], v[74:75], off offset:128
	global_load_dwordx4 v[242:245], v[74:75], off offset:192
	v_lshl_add_u64 v[74:75], v[74:75], 0, s[0:1]
	s_waitcnt vmcnt(20)
	v_mfma_f32_16x16x32_bf16 v[24:27], v[102:105], v[68:71], v[24:27]
	v_mfma_f32_16x16x32_bf16 v[24:27], v[106:109], v[76:79], v[24:27]
	v_mfma_f32_16x16x32_bf16 v[24:27], v[110:113], v[80:83], v[24:27]
	v_mfma_f32_16x16x32_bf16 v[24:27], v[114:117], v[84:87], v[24:27]
	global_load_dwordx4 v[102:105], v[74:75], off offset:0
	global_load_dwordx4 v[106:109], v[74:75], off offset:64
	global_load_dwordx4 v[110:113], v[74:75], off offset:128
	global_load_dwordx4 v[114:117], v[74:75], off offset:192
	v_lshl_add_u64 v[74:75], v[74:75], 0, s[0:1]
	s_waitcnt vmcnt(20)
	v_mfma_f32_16x16x32_bf16 v[20:23], v[118:121], v[68:71], v[20:23]
	v_mfma_f32_16x16x32_bf16 v[20:23], v[122:125], v[76:79], v[20:23]
	v_mfma_f32_16x16x32_bf16 v[20:23], v[126:129], v[80:83], v[20:23]
	v_mfma_f32_16x16x32_bf16 v[20:23], v[130:133], v[84:87], v[20:23]
	global_load_dwordx4 v[118:121], v[74:75], off offset:0
	global_load_dwordx4 v[122:125], v[74:75], off offset:64
	global_load_dwordx4 v[126:129], v[74:75], off offset:128
	global_load_dwordx4 v[130:133], v[74:75], off offset:192
	v_lshl_add_u64 v[74:75], v[74:75], 0, s[0:1]
	s_waitcnt vmcnt(20)
	v_mfma_f32_16x16x32_bf16 v[48:51], v[134:137], v[68:71], v[48:51]
	v_mfma_f32_16x16x32_bf16 v[48:51], v[138:141], v[76:79], v[48:51]
	v_mfma_f32_16x16x32_bf16 v[48:51], v[142:145], v[80:83], v[48:51]
	v_mfma_f32_16x16x32_bf16 v[48:51], v[146:149], v[84:87], v[48:51]
	global_load_dwordx4 v[134:137], v[74:75], off offset:0
	global_load_dwordx4 v[138:141], v[74:75], off offset:64
	global_load_dwordx4 v[142:145], v[74:75], off offset:128
	global_load_dwordx4 v[146:149], v[74:75], off offset:192
	v_lshl_add_u64 v[74:75], v[74:75], 0, s[0:1]
	s_waitcnt vmcnt(20)
	v_mfma_f32_16x16x32_bf16 v[44:47], v[150:153], v[68:71], v[44:47]
	v_mfma_f32_16x16x32_bf16 v[44:47], v[154:157], v[76:79], v[44:47]
	v_mfma_f32_16x16x32_bf16 v[44:47], v[158:161], v[80:83], v[44:47]
	v_mfma_f32_16x16x32_bf16 v[44:47], v[162:165], v[84:87], v[44:47]
	global_load_dwordx4 v[150:153], v[74:75], off offset:0
	global_load_dwordx4 v[154:157], v[74:75], off offset:64
	global_load_dwordx4 v[158:161], v[74:75], off offset:128
	global_load_dwordx4 v[162:165], v[74:75], off offset:192
	s_waitcnt vmcnt(20)
	v_mfma_f32_16x16x32_bf16 v[40:43], v[214:217], v[68:71], v[40:43]
	v_mfma_f32_16x16x32_bf16 v[40:43], v[218:221], v[76:79], v[40:43]
	v_mfma_f32_16x16x32_bf16 v[40:43], v[222:225], v[80:83], v[40:43]
	v_mfma_f32_16x16x32_bf16 v[40:43], v[226:229], v[84:87], v[40:43]
	s_waitcnt vmcnt(16)
	v_mfma_f32_16x16x32_bf16 v[36:39], v[230:233], v[68:71], v[36:39]
	v_mfma_f32_16x16x32_bf16 v[36:39], v[234:237], v[76:79], v[36:39]
	v_mfma_f32_16x16x32_bf16 v[36:39], v[238:241], v[80:83], v[36:39]
	v_mfma_f32_16x16x32_bf16 v[36:39], v[242:245], v[84:87], v[36:39]
	s_waitcnt vmcnt(12)
	v_mfma_f32_16x16x32_bf16 v[64:67], v[102:105], v[68:71], v[64:67]
	v_mfma_f32_16x16x32_bf16 v[64:67], v[106:109], v[76:79], v[64:67]
	v_mfma_f32_16x16x32_bf16 v[64:67], v[110:113], v[80:83], v[64:67]
	v_mfma_f32_16x16x32_bf16 v[64:67], v[114:117], v[84:87], v[64:67]
	s_waitcnt vmcnt(8)
	v_mfma_f32_16x16x32_bf16 v[60:63], v[118:121], v[68:71], v[60:63]
	v_mfma_f32_16x16x32_bf16 v[60:63], v[122:125], v[76:79], v[60:63]
	v_mfma_f32_16x16x32_bf16 v[60:63], v[126:129], v[80:83], v[60:63]
	v_mfma_f32_16x16x32_bf16 v[60:63], v[130:133], v[84:87], v[60:63]
	s_waitcnt vmcnt(4)
	v_mfma_f32_16x16x32_bf16 v[56:59], v[134:137], v[68:71], v[56:59]
	v_mfma_f32_16x16x32_bf16 v[56:59], v[138:141], v[76:79], v[56:59]
	v_mfma_f32_16x16x32_bf16 v[56:59], v[142:145], v[80:83], v[56:59]
	v_mfma_f32_16x16x32_bf16 v[56:59], v[146:149], v[84:87], v[56:59]
	s_waitcnt vmcnt(0)
	v_mfma_f32_16x16x32_bf16 v[52:55], v[150:153], v[68:71], v[52:55]
	v_mfma_f32_16x16x32_bf16 v[52:55], v[154:157], v[76:79], v[52:55]
	v_mfma_f32_16x16x32_bf16 v[52:55], v[158:161], v[80:83], v[52:55]
	v_mfma_f32_16x16x32_bf16 v[52:55], v[162:165], v[84:87], v[52:55]
	s_nop 7
	global_store_dwordx4 v[88:89], v[16:19], off
	global_store_dwordx4 v[88:89], v[12:15], off offset:256
	global_store_dwordx4 v[88:89], v[8:11], off offset:512
	global_store_dwordx4 v[88:89], v[4:7], off offset:768
	global_store_dwordx4 v[88:89], v[32:35], off offset:1024
	global_store_dwordx4 v[88:89], v[28:31], off offset:1280
	global_store_dwordx4 v[88:89], v[24:27], off offset:1536
	global_store_dwordx4 v[88:89], v[20:23], off offset:1792
	global_store_dwordx4 v[88:89], v[48:51], off offset:2048
	global_store_dwordx4 v[88:89], v[44:47], off offset:2304
	global_store_dwordx4 v[88:89], v[40:43], off offset:2560
	global_store_dwordx4 v[88:89], v[36:39], off offset:2816
	global_store_dwordx4 v[88:89], v[64:67], off offset:3072
	global_store_dwordx4 v[88:89], v[60:63], off offset:3328
	global_store_dwordx4 v[88:89], v[56:59], off offset:3584
	global_store_dwordx4 v[88:89], v[52:55], off offset:3840
